# LayerNorm row loops (LN+modulate x2, final LN): gamma/beta hoisted, modulation vectors requested up front, next row prefetched (2 buffers, unroll 2)
# speedup vs baseline: 1.0544x; 1.0032x over previous
; DI float lo16(unsigned w) { return __uint_as_float(w << 16); }
; DI float hi16(unsigned w) { return __uint_as_float(w & 0xffff0000u); }
; DI float wave_sum(float v) { for (int o = 32; o >= 1; o >>= 1) v += __shfl_xor(v, o); return v; }
; DI int get_tid() { int t = (int)threadIdx.x; asm volatile("" : "+v"(t)); return t; }
; DI void ln_pass(CP c, int mode, const float* gam, const float* bet, const float* modsc, const float* modsh, int bid, int nb, bool fin) {
;     const int tid = get_tid(), lane = tid & 63, wave = tid >> 6;
;     bf16_t* XB = (bf16_t*)(c->ws + WS_XB); bf16_t* H = (bf16_t*)(c->ws + WS_H);
;     for (int r = bid * 8 + wave; r < MT; r += nb * 8) {
;         f32x4 v[4];
;         if (mode == 0) { const float* src = r < MP ? c->in[I_XP] + (size_t)r * DM : c->in[I_XS] + (size_t)(r - MP) * DM;
; #pragma unroll
;             for (int i = 0; i < 4; ++i) v[i] = *(const f32x4*)(src + lane * 4 + 256 * i); }
;         else {
; #pragma unroll
;             for (int i = 0; i < 4; ++i) { const u32x2 w = *(const u32x2*)(XB + (size_t)r * DM + lane * 4 + 256 * i); v[i] = (f32x4){lo16(w.x), hi16(w.x), lo16(w.y), hi16(w.y)}; } }
;         if (mode != 1) {
;             float s = 0.f;
; #pragma unroll
;             for (int i = 0; i < 4; ++i) s += v[i][0] + v[i][1] + v[i][2] + v[i][3];
;             const float mean = wave_sum(s) * (1.f / 1024.f); float q = 0.f;
; #pragma unroll
;             for (int i = 0; i < 4; ++i) { const f32x4 d = v[i] - mean; q += d[0] * d[0] + d[1] * d[1] + d[2] * d[2] + d[3] * d[3]; }
;             const float rstd = rsqrtf(wave_sum(q) * (1.f / 1024.f) + 1e-5f);
.LBB0_403:
	s_waitcnt lgkmcnt(0)
	v_readlane_b32 s6, v254, 30
	v_readlane_b32 s7, v254, 31
	s_ashr_i32 s7, s6, 31
	v_writelane_b32 v254, s6, 30
	s_nop 1
	v_writelane_b32 v254, s7, 31
	s_lshl_b32 s6, s6, 5
	v_writelane_b32 v255, s6, 6
	s_cmp_lt_i32 s80, 7
	s_mov_b64 s[6:7], -1
	s_cbranch_scc1 .LBB0_498
	s_cmp_lt_i32 s80, 9
	s_cbranch_scc1 .LBB0_491
	s_cmp_lt_i32 s80, 11
	s_cbranch_scc1 .LBB0_428
	s_cmp_eq_u32 s80, 11
	s_cbranch_scc0 .LBB0_427
	s_load_dwordx4 s[40:43], s[46:47], 0x118
	s_and_b64 vcc, exec, s[0:1]
	s_cbranch_vccz .LBB0_412
	s_waitcnt vmcnt(0)
	v_mov_b32_e32 v4, v188
	v_readlane_b32 s0, v252, 39
	v_ashrrev_i32_e32 v2, 6, v4
	v_readlane_b32 s1, v252, 40
	v_add_u32_e32 v46, s0, v2
	s_movk_i32 s0, 0x4200
	v_cmp_gt_i32_e32 vcc, s0, v46
	s_and_saveexec_b64 s[0:1], vcc
	s_mov_b32 s12, 0x800000
	s_cbranch_execz .LBB0_411
	s_waitcnt lgkmcnt(0)
	s_add_u32 s6, s42, 0x1000
	s_addc_u32 s7, s43, 0
	v_lshlrev_b32_e32 v0, 4, v4
	s_add_u32 s8, s40, 0x1000
	v_and_b32_e32 v0, 0x3f0, v0
	s_addc_u32 s9, s41, 0
	v_or_b32_e32 v6, 0x400, v0
	v_mov_b32_e32 v7, v1
	v_lshl_add_u64 v[10:11], s[8:9], 0, v[0:1]
	v_lshl_add_u64 v[12:13], s[6:7], 0, v[0:1]
	v_lshl_add_u64 v[14:15], s[8:9], 0, v[6:7]
	v_lshl_add_u64 v[16:17], s[6:7], 0, v[6:7]
	v_or_b32_e32 v6, 0x800, v0
	v_or_b32_e32 v0, 0xc00, v0
	v_lshl_add_u64 v[22:23], s[8:9], 0, v[0:1]
	v_lshl_add_u64 v[24:25], s[6:7], 0, v[0:1]
	v_and_b32_e32 v0, 64, v196
	v_add_u32_e32 v0, 64, v0
	v_xor_b32_e32 v3, 32, v196
	v_cmp_lt_i32_e32 vcc, v3, v0
	v_lshl_add_u64 v[18:19], s[8:9], 0, v[6:7]
	v_lshl_add_u64 v[20:21], s[6:7], 0, v[6:7]
	v_cndmask_b32_e32 v3, v196, v3, vcc
	v_lshlrev_b32_e32 v47, 2, v3
	v_xor_b32_e32 v3, 16, v196
	v_cmp_lt_i32_e32 vcc, v3, v0
	s_load_dwordx2 s[6:7], s[46:47], 0x128
	v_readlane_b32 s8, v252, 39
	v_cndmask_b32_e32 v3, v196, v3, vcc
	v_lshlrev_b32_e32 v48, 2, v3
	v_xor_b32_e32 v3, 8, v196
	v_cmp_lt_i32_e32 vcc, v3, v0
	v_readlane_b32 s9, v252, 40
	s_nop 0
	v_cndmask_b32_e32 v3, v196, v3, vcc
	v_lshlrev_b32_e32 v49, 2, v3
	v_xor_b32_e32 v3, 4, v196
	v_cmp_lt_i32_e32 vcc, v3, v0
	s_nop 1
	v_cndmask_b32_e32 v3, v196, v3, vcc
	v_lshlrev_b32_e32 v50, 2, v3
	v_xor_b32_e32 v3, 2, v196
	v_cmp_lt_i32_e32 vcc, v3, v0
	s_nop 1
	v_cndmask_b32_e32 v3, v196, v3, vcc
	v_lshlrev_b32_e32 v51, 2, v3
	v_xor_b32_e32 v3, 1, v196
	v_cmp_lt_i32_e32 vcc, v3, v0
	s_nop 1
	v_cndmask_b32_e32 v0, v196, v3, vcc
	v_ashrrev_i32_e32 v3, 31, v2
	v_lshl_add_u64 v[2:3], s[8:9], 0, v[2:3]
	v_lshlrev_b32_e32 v52, 2, v0
	v_lshlrev_b64 v[6:7], 11, v[2:3]
	v_and_b32_e32 v0, 63, v4
	v_lshlrev_b64 v[2:3], 12, v[2:3]
	v_lshl_or_b32 v6, v0, 3, v6
	v_lshl_or_b32 v2, v0, 4, v2
	v_lshl_add_u64 v[4:5], s[20:21], 0, v[6:7]
	s_mov_b64 s[8:9], 0x1c706400
	s_waitcnt lgkmcnt(0)
	v_lshl_add_u64 v[2:3], s[6:7], 0, v[2:3]
	s_mov_b64 s[6:7], 0xc00
	v_lshl_add_u64 v[26:27], v[4:5], 0, s[8:9]
	v_lshl_add_u64 v[28:29], v[2:3], 0, s[6:7]
	s_mov_b64 s[6:7], 0
	global_load_dwordx4 v[60:63], v[10:11], off
	global_load_dwordx4 v[64:67], v[14:15], off
	global_load_dwordx4 v[68:71], v[18:19], off
	global_load_dwordx4 v[72:75], v[22:23], off
	global_load_dwordx4 v[76:79], v[12:13], off
	global_load_dwordx4 v[80:83], v[16:17], off
	global_load_dwordx4 v[84:87], v[20:21], off
	global_load_dwordx4 v[88:91], v[24:25], off
	global_load_dwordx2 v[92:93], v[26:27], off offset:-1024
	global_load_dwordx2 v[94:95], v[26:27], off offset:-512
	global_load_dwordx2 v[96:97], v[26:27], off
	global_load_dwordx2 v[98:99], v[26:27], off offset:512
.LBB0_410:
	v_lshl_add_u64 v[56:57], v[26:27], 0, s[44:45]
	global_load_dwordx2 v[100:101], v[56:57], off offset:-1024
	global_load_dwordx2 v[102:103], v[56:57], off offset:-512
	global_load_dwordx2 v[104:105], v[56:57], off
	global_load_dwordx2 v[106:107], v[56:57], off offset:512
	s_waitcnt vmcnt(4)
	v_lshlrev_b32_e32 v140, 16, v92
	v_and_b32_e32 v141, 0xffff0000, v92
	v_lshlrev_b32_e32 v142, 16, v93
	v_and_b32_e32 v143, 0xffff0000, v93
	v_lshlrev_b32_e32 v144, 16, v94
	v_and_b32_e32 v145, 0xffff0000, v94
	v_lshlrev_b32_e32 v146, 16, v95
	v_and_b32_e32 v147, 0xffff0000, v95
	v_lshlrev_b32_e32 v148, 16, v96
	v_and_b32_e32 v149, 0xffff0000, v96
	v_lshlrev_b32_e32 v150, 16, v97
	v_and_b32_e32 v151, 0xffff0000, v97
	v_lshlrev_b32_e32 v152, 16, v98
	v_and_b32_e32 v153, 0xffff0000, v98
	v_lshlrev_b32_e32 v154, 16, v99
	v_and_b32_e32 v155, 0xffff0000, v99
	v_add_f32_e32 v0, v140, v141
	v_add_f32_e32 v0, v0, v142
	v_add_f32_e32 v0, v0, v143
	v_add_f32_e32 v0, v0, v144
	v_add_f32_e32 v0, v0, v145
	v_add_f32_e32 v0, v0, v146
	v_add_f32_e32 v0, v0, v147
	v_add_f32_e32 v0, v0, v148
	v_add_f32_e32 v0, v0, v149
	v_add_f32_e32 v0, v0, v150
	v_add_f32_e32 v0, v0, v151
	v_add_f32_e32 v0, v0, v152
	v_add_f32_e32 v0, v0, v153
	v_add_f32_e32 v0, v0, v154
	v_add_f32_e32 v0, v0, v155
	ds_bpermute_b32 v54, v47, v0
	s_waitcnt lgkmcnt(0)
	v_add_f32_e32 v0, v0, v54
	ds_bpermute_b32 v54, v48, v0
	s_waitcnt lgkmcnt(0)
	v_add_f32_e32 v0, v0, v54
	ds_bpermute_b32 v54, v49, v0
	s_waitcnt lgkmcnt(0)
	v_add_f32_e32 v0, v0, v54
	ds_bpermute_b32 v54, v50, v0
	s_waitcnt lgkmcnt(0)
	v_add_f32_e32 v0, v0, v54
	ds_bpermute_b32 v54, v51, v0
	s_waitcnt lgkmcnt(0)
	v_add_f32_e32 v0, v0, v54
	ds_bpermute_b32 v54, v52, v0
	s_waitcnt lgkmcnt(0)
; DI unsigned pk2(float lo, float hi) { const hwf2_t v = {lo, hi}; const hwbf2_t b = __builtin_convertvector(v, hwbf2_t); return __builtin_bit_cast(unsigned, b); }
; DI float wave_sum(float v) { for (int o = 32; o >= 1; o >>= 1) v += __shfl_xor(v, o); return v; }
; DI void ln_pass(CP c, int mode, const float* gam, const float* bet, const float* modsc, const float* modsh, int bid, int nb, bool fin) {
;     ...
;             const float mean = wave_sum(s) * (1.f / 1024.f); float q = 0.f;
; #pragma unroll
;             for (int i = 0; i < 4; ++i) { const f32x4 d = v[i] - mean; q += d[0] * d[0] + d[1] * d[1] + d[2] * d[2] + d[3] * d[3]; }
;             const float rstd = rsqrtf(wave_sum(q) * (1.f / 1024.f) + 1e-5f);
; #pragma unroll
;             for (int i = 0; i < 4; ++i) { const int col = lane * 4 + 256 * i; const f32x4 g = *(const f32x4*)(gam + col), b = *(const f32x4*)(bet + col);
;                 v[i] = (v[i] - mean) * rstd * g + b;
;                 if (fin) *(f32x4*)(c->out + (size_t)r * DM + col) = v[i];
;                 else { u32x2 w; w.x = pk2(v[i][0], v[i][1]); w.y = pk2(v[i][2], v[i][3]); *(u32x2*)(XB + (size_t)r * DM + col) = w; } }
	v_add_f32_e32 v0, v0, v54
	v_fmac_f32_e32 v140, 0xba800000, v0
	v_fmac_f32_e32 v141, 0xba800000, v0
	v_fmac_f32_e32 v142, 0xba800000, v0
	v_fmac_f32_e32 v143, 0xba800000, v0
	v_fmac_f32_e32 v144, 0xba800000, v0
	v_fmac_f32_e32 v145, 0xba800000, v0
	v_fmac_f32_e32 v146, 0xba800000, v0
	v_fmac_f32_e32 v147, 0xba800000, v0
	v_fmac_f32_e32 v148, 0xba800000, v0
	v_fmac_f32_e32 v149, 0xba800000, v0
	v_fmac_f32_e32 v150, 0xba800000, v0
	v_fmac_f32_e32 v151, 0xba800000, v0
	v_fmac_f32_e32 v152, 0xba800000, v0
	v_fmac_f32_e32 v153, 0xba800000, v0
	v_fmac_f32_e32 v154, 0xba800000, v0
	v_fmac_f32_e32 v155, 0xba800000, v0
	v_mul_f32_e32 v55, v140, v140
	v_fmac_f32_e32 v55, v141, v141
	v_fmac_f32_e32 v55, v142, v142
	v_fmac_f32_e32 v55, v143, v143
	v_fmac_f32_e32 v55, v144, v144
	v_fmac_f32_e32 v55, v145, v145
	v_fmac_f32_e32 v55, v146, v146
	v_fmac_f32_e32 v55, v147, v147
	v_fmac_f32_e32 v55, v148, v148
	v_fmac_f32_e32 v55, v149, v149
	v_fmac_f32_e32 v55, v150, v150
	v_fmac_f32_e32 v55, v151, v151
	v_fmac_f32_e32 v55, v152, v152
	v_fmac_f32_e32 v55, v153, v153
	v_fmac_f32_e32 v55, v154, v154
	v_fmac_f32_e32 v55, v155, v155
	ds_bpermute_b32 v54, v47, v55
	s_waitcnt lgkmcnt(0)
	v_add_f32_e32 v55, v55, v54
	ds_bpermute_b32 v54, v48, v55
	s_waitcnt lgkmcnt(0)
	v_add_f32_e32 v55, v55, v54
	ds_bpermute_b32 v54, v49, v55
	s_waitcnt lgkmcnt(0)
	v_add_f32_e32 v55, v55, v54
	ds_bpermute_b32 v54, v50, v55
	s_waitcnt lgkmcnt(0)
	v_add_f32_e32 v55, v55, v54
	ds_bpermute_b32 v54, v51, v55
	s_waitcnt lgkmcnt(0)
	v_add_f32_e32 v55, v55, v54
	ds_bpermute_b32 v54, v52, v55
	s_waitcnt lgkmcnt(0)
	v_add_f32_e32 v55, v55, v54
	v_fmamk_f32 v55, v55, 0x3a800000, v189
	v_rsq_f32_e32 v55, v55
	s_nop 0
	v_mul_f32_e32 v140, v140, v55
	v_mul_f32_e32 v141, v141, v55
	v_mul_f32_e32 v142, v142, v55
	v_mul_f32_e32 v143, v143, v55
	v_mul_f32_e32 v144, v144, v55
	v_mul_f32_e32 v145, v145, v55
	v_mul_f32_e32 v146, v146, v55
	v_mul_f32_e32 v147, v147, v55
	v_mul_f32_e32 v148, v148, v55
	v_mul_f32_e32 v149, v149, v55
	v_mul_f32_e32 v150, v150, v55
	v_mul_f32_e32 v151, v151, v55
	v_mul_f32_e32 v152, v152, v55
	v_mul_f32_e32 v153, v153, v55
	v_mul_f32_e32 v154, v154, v55
	v_mul_f32_e32 v155, v155, v55
	v_fma_f32 v140, v60, v140, v76
	v_fma_f32 v141, v61, v141, v77
	v_fma_f32 v142, v62, v142, v78
	v_fma_f32 v143, v63, v143, v79
	v_fma_f32 v144, v64, v144, v80
	v_fma_f32 v145, v65, v145, v81
	v_fma_f32 v146, v66, v146, v82
	v_fma_f32 v147, v67, v147, v83
	v_fma_f32 v148, v68, v148, v84
	v_fma_f32 v149, v69, v149, v85
	v_fma_f32 v150, v70, v150, v86
	v_fma_f32 v151, v71, v151, v87
	v_fma_f32 v152, v72, v152, v88
	v_fma_f32 v153, v73, v153, v89
	v_fma_f32 v154, v74, v154, v90
	v_fma_f32 v155, v75, v155, v91
	global_store_dwordx4 v[28:29], v[140:143], off offset:-3072
	global_store_dwordx4 v[28:29], v[144:147], off offset:-2048
	global_store_dwordx4 v[28:29], v[148:151], off offset:-1024
	global_store_dwordx4 v[28:29], v[152:155], off
	v_add_u32_e32 v46, s76, v46
	v_mov_b32_e32 v26, v56
	v_mov_b32_e32 v27, v57
	v_lshl_add_u64 v[28:29], v[28:29], 0, s[30:31]
	v_cmp_lt_i32_e32 vcc, s81, v46
	s_or_b64 s[6:7], vcc, s[6:7]
	s_andn2_b64 exec, exec, s[6:7]
	s_cbranch_execz .LBB0_411
; DI unsigned pk2(float lo, float hi) { const hwf2_t v = {lo, hi}; const hwbf2_t b = __builtin_convertvector(v, hwbf2_t); return __builtin_bit_cast(unsigned, b); }
; DI float lo16(unsigned w) { return __uint_as_float(w << 16); }
; DI float hi16(unsigned w) { return __uint_as_float(w & 0xffff0000u); }
; DI float wave_sum(float v) { for (int o = 32; o >= 1; o >>= 1) v += __shfl_xor(v, o); return v; }
; DI void ln_pass(CP c, int mode, const float* gam, const float* bet, const float* modsc, const float* modsh, int bid, int nb, bool fin) {
;     ...
;     for (int r = bid * 8 + wave; r < MT; r += nb * 8) {
;         f32x4 v[4];
;         if (mode == 0) { const float* src = r < MP ? c->in[I_XP] + (size_t)r * DM : c->in[I_XS] + (size_t)(r - MP) * DM;
; #pragma unroll
;             for (int i = 0; i < 4; ++i) v[i] = *(const f32x4*)(src + lane * 4 + 256 * i); }
;         else {
; #pragma unroll
;             for (int i = 0; i < 4; ++i) { const u32x2 w = *(const u32x2*)(XB + (size_t)r * DM + lane * 4 + 256 * i); v[i] = (f32x4){lo16(w.x), hi16(w.x), lo16(w.y), hi16(w.y)}; } }
;         if (mode != 1) {
;             float s = 0.f;
; #pragma unroll
;             for (int i = 0; i < 4; ++i) s += v[i][0] + v[i][1] + v[i][2] + v[i][3];
;             const float mean = wave_sum(s) * (1.f / 1024.f); float q = 0.f;
; #pragma unroll
;             for (int i = 0; i < 4; ++i) { const f32x4 d = v[i] - mean; q += d[0] * d[0] + d[1] * d[1] + d[2] * d[2] + d[3] * d[3]; }
;             const float rstd = rsqrtf(wave_sum(q) * (1.f / 1024.f) + 1e-5f);
; #pragma unroll
;             for (int i = 0; i < 4; ++i) { const int col = lane * 4 + 256 * i; const f32x4 g = *(const f32x4*)(gam + col), b = *(const f32x4*)(bet + col);
;                 v[i] = (v[i] - mean) * rstd * g + b;
;                 if (fin) *(f32x4*)(c->out + (size_t)r * DM + col) = v[i];
;                 else { u32x2 w; w.x = pk2(v[i][0], v[i][1]); w.y = pk2(v[i][2], v[i][3]); *(u32x2*)(XB + (size_t)r * DM + col) = w; } }
	v_lshl_add_u64 v[56:57], v[26:27], 0, s[44:45]
	global_load_dwordx2 v[92:93], v[56:57], off offset:-1024
	global_load_dwordx2 v[94:95], v[56:57], off offset:-512
	global_load_dwordx2 v[96:97], v[56:57], off
	global_load_dwordx2 v[98:99], v[56:57], off offset:512
	s_waitcnt vmcnt(4)
	v_lshlrev_b32_e32 v140, 16, v100
	v_and_b32_e32 v141, 0xffff0000, v100
	v_lshlrev_b32_e32 v142, 16, v101
	v_and_b32_e32 v143, 0xffff0000, v101
	v_lshlrev_b32_e32 v144, 16, v102
	v_and_b32_e32 v145, 0xffff0000, v102
	v_lshlrev_b32_e32 v146, 16, v103
	v_and_b32_e32 v147, 0xffff0000, v103
	v_lshlrev_b32_e32 v148, 16, v104
	v_and_b32_e32 v149, 0xffff0000, v104
	v_lshlrev_b32_e32 v150, 16, v105
	v_and_b32_e32 v151, 0xffff0000, v105
	v_lshlrev_b32_e32 v152, 16, v106
	v_and_b32_e32 v153, 0xffff0000, v106
	v_lshlrev_b32_e32 v154, 16, v107
	v_and_b32_e32 v155, 0xffff0000, v107
	v_add_f32_e32 v0, v140, v141
	v_add_f32_e32 v0, v0, v142
	v_add_f32_e32 v0, v0, v143
	v_add_f32_e32 v0, v0, v144
	v_add_f32_e32 v0, v0, v145
	v_add_f32_e32 v0, v0, v146
	v_add_f32_e32 v0, v0, v147
	v_add_f32_e32 v0, v0, v148
	v_add_f32_e32 v0, v0, v149
	v_add_f32_e32 v0, v0, v150
	v_add_f32_e32 v0, v0, v151
	v_add_f32_e32 v0, v0, v152
	v_add_f32_e32 v0, v0, v153
	v_add_f32_e32 v0, v0, v154
	v_add_f32_e32 v0, v0, v155
	ds_bpermute_b32 v54, v47, v0
	s_waitcnt lgkmcnt(0)
	v_add_f32_e32 v0, v0, v54
	ds_bpermute_b32 v54, v48, v0
	s_waitcnt lgkmcnt(0)
	v_add_f32_e32 v0, v0, v54
	ds_bpermute_b32 v54, v49, v0
	s_waitcnt lgkmcnt(0)
	v_add_f32_e32 v0, v0, v54
	ds_bpermute_b32 v54, v50, v0
	s_waitcnt lgkmcnt(0)
	v_add_f32_e32 v0, v0, v54
	ds_bpermute_b32 v54, v51, v0
	s_waitcnt lgkmcnt(0)
	v_add_f32_e32 v0, v0, v54
	ds_bpermute_b32 v54, v52, v0
	s_waitcnt lgkmcnt(0)
	v_add_f32_e32 v0, v0, v54
	v_fmac_f32_e32 v140, 0xba800000, v0
	v_fmac_f32_e32 v141, 0xba800000, v0
	v_fmac_f32_e32 v142, 0xba800000, v0
	v_fmac_f32_e32 v143, 0xba800000, v0
	v_fmac_f32_e32 v144, 0xba800000, v0
	v_fmac_f32_e32 v145, 0xba800000, v0
	v_fmac_f32_e32 v146, 0xba800000, v0
	v_fmac_f32_e32 v147, 0xba800000, v0
	v_fmac_f32_e32 v148, 0xba800000, v0
	v_fmac_f32_e32 v149, 0xba800000, v0
	v_fmac_f32_e32 v150, 0xba800000, v0
	v_fmac_f32_e32 v151, 0xba800000, v0
	v_fmac_f32_e32 v152, 0xba800000, v0
	v_fmac_f32_e32 v153, 0xba800000, v0
	v_fmac_f32_e32 v154, 0xba800000, v0
	v_fmac_f32_e32 v155, 0xba800000, v0
	v_mul_f32_e32 v55, v140, v140
	v_fmac_f32_e32 v55, v141, v141
	v_fmac_f32_e32 v55, v142, v142
	v_fmac_f32_e32 v55, v143, v143
	v_fmac_f32_e32 v55, v144, v144
	v_fmac_f32_e32 v55, v145, v145
	v_fmac_f32_e32 v55, v146, v146
	v_fmac_f32_e32 v55, v147, v147
	v_fmac_f32_e32 v55, v148, v148
	v_fmac_f32_e32 v55, v149, v149
	v_fmac_f32_e32 v55, v150, v150
	v_fmac_f32_e32 v55, v151, v151
	v_fmac_f32_e32 v55, v152, v152
	v_fmac_f32_e32 v55, v153, v153
	v_fmac_f32_e32 v55, v154, v154
	v_fmac_f32_e32 v55, v155, v155
	ds_bpermute_b32 v54, v47, v55
	s_waitcnt lgkmcnt(0)
	v_add_f32_e32 v55, v55, v54
	ds_bpermute_b32 v54, v48, v55
	s_waitcnt lgkmcnt(0)
	v_add_f32_e32 v55, v55, v54
	ds_bpermute_b32 v54, v49, v55
	s_waitcnt lgkmcnt(0)
	v_add_f32_e32 v55, v55, v54
	ds_bpermute_b32 v54, v50, v55
	s_waitcnt lgkmcnt(0)
	v_add_f32_e32 v55, v55, v54
	ds_bpermute_b32 v54, v51, v55
	s_waitcnt lgkmcnt(0)
	v_add_f32_e32 v55, v55, v54
	ds_bpermute_b32 v54, v52, v55
	s_waitcnt lgkmcnt(0)
	v_add_f32_e32 v55, v55, v54
	v_fmamk_f32 v55, v55, 0x3a800000, v189
	v_rsq_f32_e32 v55, v55
	s_nop 0
	v_mul_f32_e32 v140, v140, v55
	v_mul_f32_e32 v141, v141, v55
	v_mul_f32_e32 v142, v142, v55
	v_mul_f32_e32 v143, v143, v55
	v_mul_f32_e32 v144, v144, v55
	v_mul_f32_e32 v145, v145, v55
	v_mul_f32_e32 v146, v146, v55
	v_mul_f32_e32 v147, v147, v55
	v_mul_f32_e32 v148, v148, v55
	v_mul_f32_e32 v149, v149, v55
	v_mul_f32_e32 v150, v150, v55
	v_mul_f32_e32 v151, v151, v55
	v_mul_f32_e32 v152, v152, v55
	v_mul_f32_e32 v153, v153, v55
	v_mul_f32_e32 v154, v154, v55
	v_mul_f32_e32 v155, v155, v55
	v_fma_f32 v140, v60, v140, v76
	v_fma_f32 v141, v61, v141, v77
	v_fma_f32 v142, v62, v142, v78
	v_fma_f32 v143, v63, v143, v79
	v_fma_f32 v144, v64, v144, v80
	v_fma_f32 v145, v65, v145, v81
	v_fma_f32 v146, v66, v146, v82
	v_fma_f32 v147, v67, v147, v83
	v_fma_f32 v148, v68, v148, v84
	v_fma_f32 v149, v69, v149, v85
	v_fma_f32 v150, v70, v150, v86
	v_fma_f32 v151, v71, v151, v87
	v_fma_f32 v152, v72, v152, v88
	v_fma_f32 v153, v73, v153, v89
	v_fma_f32 v154, v74, v154, v90
	v_fma_f32 v155, v75, v155, v91
	global_store_dwordx4 v[28:29], v[140:143], off offset:-3072
	global_store_dwordx4 v[28:29], v[144:147], off offset:-2048
	global_store_dwordx4 v[28:29], v[148:151], off offset:-1024
	global_store_dwordx4 v[28:29], v[152:155], off
	v_add_u32_e32 v46, s76, v46
	v_mov_b32_e32 v26, v56
	v_mov_b32_e32 v27, v57
	v_lshl_add_u64 v[28:29], v[28:29], 0, s[30:31]
	v_cmp_lt_i32_e32 vcc, s81, v46
	s_or_b64 s[6:7], vcc, s[6:7]
	s_andn2_b64 exec, exec, s[6:7]
	s_cbranch_execnz .LBB0_410

; DI unsigned pk2(float lo, float hi) { const hwf2_t v = {lo, hi}; const hwbf2_t b = __builtin_convertvector(v, hwbf2_t); return __builtin_bit_cast(unsigned, b); }
; DI float lo16(unsigned w) { return __uint_as_float(w << 16); }
; DI float hi16(unsigned w) { return __uint_as_float(w & 0xffff0000u); }
; DI float wave_sum(float v) { for (int o = 32; o >= 1; o >>= 1) v += __shfl_xor(v, o); return v; }
; DI void ln_pass(CP c, int mode, const float* gam, const float* bet, const float* modsc, const float* modsh, int bid, int nb, bool fin) {
;     ...
;     for (int r = bid * 8 + wave; r < MT; r += nb * 8) {
;         f32x4 v[4];
;         if (mode == 0) { const float* src = r < MP ? c->in[I_XP] + (size_t)r * DM : c->in[I_XS] + (size_t)(r - MP) * DM;
; #pragma unroll
;             for (int i = 0; i < 4; ++i) v[i] = *(const f32x4*)(src + lane * 4 + 256 * i); }
;         else {
; #pragma unroll
;             for (int i = 0; i < 4; ++i) { const u32x2 w = *(const u32x2*)(XB + (size_t)r * DM + lane * 4 + 256 * i); v[i] = (f32x4){lo16(w.x), hi16(w.x), lo16(w.y), hi16(w.y)}; } }
;         if (mode != 1) {
;             float s = 0.f;
; #pragma unroll
;             for (int i = 0; i < 4; ++i) s += v[i][0] + v[i][1] + v[i][2] + v[i][3];
;             const float mean = wave_sum(s) * (1.f / 1024.f); float q = 0.f;
; #pragma unroll
;             for (int i = 0; i < 4; ++i) { const f32x4 d = v[i] - mean; q += d[0] * d[0] + d[1] * d[1] + d[2] * d[2] + d[3] * d[3]; }
;             const float rstd = rsqrtf(wave_sum(q) * (1.f / 1024.f) + 1e-5f);
; #pragma unroll
;             for (int i = 0; i < 4; ++i) { const int col = lane * 4 + 256 * i; const f32x4 g = *(const f32x4*)(gam + col), b = *(const f32x4*)(bet + col);
;                 v[i] = (v[i] - mean) * rstd * g + b;
;                 if (fin) *(f32x4*)(c->out + (size_t)r * DM + col) = v[i];
;                 else { u32x2 w; w.x = pk2(v[i][0], v[i][1]); w.y = pk2(v[i][2], v[i][3]); *(u32x2*)(XB + (size_t)r * DM + col) = w; } }
;         }
;         if (modsc) { const int mr = modrow_of(r);
; #pragma unroll
;             for (int i = 0; i < 4; ++i) { const int col = lane * 4 + 256 * i; const f32x4 sc = *(const f32x4*)(modsc + (size_t)mr * 12288 + col), sh = *(const f32x4*)(modsh + (size_t)mr * 12288 + col);
.LBB0_412:
	s_andn2_b64 vcc, exec, s[6:7]
	s_cbranch_vccnz .LBB0_427
	v_mov_b32_e32 v12, v188
	v_readlane_b32 s0, v252, 39
	s_waitcnt vmcnt(0)
	v_ashrrev_i32_e32 v10, 6, v12
	v_readlane_b32 s1, v252, 40
	v_add_u32_e32 v30, s0, v10
	s_movk_i32 s0, 0x4200
	v_cmp_gt_i32_e32 vcc, s0, v30
	s_and_saveexec_b64 s[0:1], vcc
	s_mov_b32 s12, 0x800000
	s_cbranch_execz .LBB0_416
	v_and_b32_e32 v6, 64, v196
	v_add_u32_e32 v6, 64, v6
	v_xor_b32_e32 v7, 32, v196
	v_cmp_lt_i32_e32 vcc, v7, v6
	v_lshlrev_b32_e32 v0, 4, v12
	v_and_b32_e32 v0, 0x3f0, v0
	v_cndmask_b32_e32 v7, v196, v7, vcc
	v_lshlrev_b32_e32 v31, 2, v7
	v_xor_b32_e32 v7, 16, v196
	v_cmp_lt_i32_e32 vcc, v7, v6
	v_lshl_add_u64 v[8:9], s[20:21], 0, v[0:1]
	s_mov_b64 s[6:7], 0xb000
	v_cndmask_b32_e32 v7, v196, v7, vcc
	v_lshlrev_b32_e32 v32, 2, v7
	v_xor_b32_e32 v7, 8, v196
	v_cmp_lt_i32_e32 vcc, v7, v6
	v_ashrrev_i32_e32 v11, 31, v10
	s_waitcnt lgkmcnt(0)
	v_lshl_add_u64 v[2:3], s[40:41], 0, v[0:1]
	v_cndmask_b32_e32 v7, v196, v7, vcc
	v_lshlrev_b32_e32 v33, 2, v7
	v_xor_b32_e32 v7, 4, v196
	v_cmp_lt_i32_e32 vcc, v7, v6
	v_lshl_add_u64 v[4:5], s[42:43], 0, v[0:1]
	v_and_b32_e32 v0, 63, v12
	v_cndmask_b32_e32 v7, v196, v7, vcc
	v_lshlrev_b32_e32 v34, 2, v7
	v_xor_b32_e32 v7, 2, v196
	v_cmp_lt_i32_e32 vcc, v7, v6
	s_nop 1
	v_cndmask_b32_e32 v7, v196, v7, vcc
	v_lshlrev_b32_e32 v35, 2, v7
	v_xor_b32_e32 v7, 1, v196
	v_cmp_lt_i32_e32 vcc, v7, v6
	s_nop 1
	v_cndmask_b32_e32 v6, v196, v7, vcc
	v_lshlrev_b32_e32 v36, 2, v6
	v_lshl_add_u64 v[6:7], v[8:9], 0, s[6:7]
	s_mov_b64 s[6:7], 0xa000
	v_lshl_add_u64 v[8:9], v[8:9], 0, s[6:7]
	v_readlane_b32 s6, v252, 39
	v_readlane_b32 s7, v252, 40
	s_nop 1
	v_lshl_add_u64 v[10:11], s[6:7], 0, v[10:11]
	v_lshlrev_b64 v[10:11], 11, v[10:11]
	v_lshl_or_b32 v10, v0, 3, v10
	v_lshl_add_u64 v[10:11], s[20:21], 0, v[10:11]
	s_mov_b64 s[6:7], 0x123c4000
	v_lshl_add_u64 v[10:11], v[10:11], 0, s[6:7]
	s_mov_b64 s[6:7], 0
	global_load_dwordx4 v[60:63], v[2:3], off
	global_load_dwordx4 v[64:67], v[2:3], off offset:1024
	global_load_dwordx4 v[68:71], v[2:3], off offset:2048
	global_load_dwordx4 v[72:75], v[2:3], off offset:3072
	global_load_dwordx4 v[76:79], v[4:5], off
	global_load_dwordx4 v[80:83], v[4:5], off offset:1024
	global_load_dwordx4 v[84:87], v[4:5], off offset:2048
	global_load_dwordx4 v[88:91], v[4:5], off offset:3072
	v_add_co_u32_e32 v12, vcc, 0xa342000, v10
	s_nop 1
	v_addc_co_u32_e32 v13, vcc, 0, v11, vcc
	global_load_dwordx2 v[92:93], v[12:13], off
	global_load_dwordx2 v[94:95], v[12:13], off offset:512
	global_load_dwordx2 v[96:97], v[12:13], off offset:1024
	global_load_dwordx2 v[98:99], v[12:13], off offset:1536
.LBB0_415:
	v_add_u32_e32 v0, 0xffffc000, v30
	v_lshrrev_b32_e32 v0, 4, v0
	v_add_u32_e32 v0, 1, v0
	v_cmp_lt_i32_e32 vcc, s3, v30
	s_nop 1
	v_cndmask_b32_e32 v0, 0, v0, vcc
	v_mad_u64_u32 v[24:25], s[8:9], v0, s86, v[6:7]
	v_mad_u64_u32 v[46:47], s[8:9], v0, s86, v[8:9]
	global_load_dwordx4 v[108:111], v[24:25], off
	global_load_dwordx4 v[112:115], v[24:25], off offset:1024
	global_load_dwordx4 v[116:119], v[24:25], off offset:2048
	global_load_dwordx4 v[120:123], v[24:25], off offset:3072
	global_load_dwordx4 v[124:127], v[46:47], off
	global_load_dwordx4 v[128:131], v[46:47], off offset:1024
	global_load_dwordx4 v[132:135], v[46:47], off offset:2048
	global_load_dwordx4 v[136:139], v[46:47], off offset:3072
	s_waitcnt vmcnt(8)
	v_lshl_add_u64 v[48:49], v[12:13], 0, s[44:45]
	global_load_dwordx2 v[100:101], v[48:49], off
	global_load_dwordx2 v[102:103], v[48:49], off offset:512
	global_load_dwordx2 v[104:105], v[48:49], off offset:1024
	global_load_dwordx2 v[106:107], v[48:49], off offset:1536
	v_lshlrev_b32_e32 v140, 16, v92
	v_and_b32_e32 v141, 0xffff0000, v92
	v_lshlrev_b32_e32 v142, 16, v93
	v_and_b32_e32 v143, 0xffff0000, v93
	v_lshlrev_b32_e32 v144, 16, v94
	v_and_b32_e32 v145, 0xffff0000, v94
	v_lshlrev_b32_e32 v146, 16, v95
	v_and_b32_e32 v147, 0xffff0000, v95
	v_lshlrev_b32_e32 v148, 16, v96
	v_and_b32_e32 v149, 0xffff0000, v96
	v_lshlrev_b32_e32 v150, 16, v97
	v_and_b32_e32 v151, 0xffff0000, v97
	v_lshlrev_b32_e32 v152, 16, v98
	v_and_b32_e32 v153, 0xffff0000, v98
	v_lshlrev_b32_e32 v154, 16, v99
	v_and_b32_e32 v155, 0xffff0000, v99
	v_add_f32_e32 v0, v140, v141
	v_add_f32_e32 v0, v0, v142
	v_add_f32_e32 v0, v0, v143
	v_add_f32_e32 v0, v0, v144
	v_add_f32_e32 v0, v0, v145
	v_add_f32_e32 v0, v0, v146
	v_add_f32_e32 v0, v0, v147
	v_add_f32_e32 v0, v0, v148
	v_add_f32_e32 v0, v0, v149
	v_add_f32_e32 v0, v0, v150
	v_add_f32_e32 v0, v0, v151
	v_add_f32_e32 v0, v0, v152
	v_add_f32_e32 v0, v0, v153
	v_add_f32_e32 v0, v0, v154
	v_add_f32_e32 v0, v0, v155
	ds_bpermute_b32 v14, v31, v0
	s_waitcnt lgkmcnt(0)
	v_add_f32_e32 v0, v0, v14
	ds_bpermute_b32 v14, v32, v0
	s_waitcnt lgkmcnt(0)
	v_add_f32_e32 v0, v0, v14
	ds_bpermute_b32 v14, v33, v0
	s_waitcnt lgkmcnt(0)
	v_add_f32_e32 v0, v0, v14
	ds_bpermute_b32 v14, v34, v0
	s_waitcnt lgkmcnt(0)
	v_add_f32_e32 v0, v0, v14
	ds_bpermute_b32 v14, v35, v0
	s_waitcnt lgkmcnt(0)
	v_add_f32_e32 v0, v0, v14
	ds_bpermute_b32 v14, v36, v0
	s_waitcnt lgkmcnt(0)
; DI unsigned pk2(float lo, float hi) { const hwf2_t v = {lo, hi}; const hwbf2_t b = __builtin_convertvector(v, hwbf2_t); return __builtin_bit_cast(unsigned, b); }
; DI float wave_sum(float v) { for (int o = 32; o >= 1; o >>= 1) v += __shfl_xor(v, o); return v; }
; DI void ln_pass(CP c, int mode, const float* gam, const float* bet, const float* modsc, const float* modsh, int bid, int nb, bool fin) {
;     ...
;         if (mode != 1) {
;             float s = 0.f;
; #pragma unroll
;             for (int i = 0; i < 4; ++i) s += v[i][0] + v[i][1] + v[i][2] + v[i][3];
;             const float mean = wave_sum(s) * (1.f / 1024.f); float q = 0.f;
; #pragma unroll
;             for (int i = 0; i < 4; ++i) { const f32x4 d = v[i] - mean; q += d[0] * d[0] + d[1] * d[1] + d[2] * d[2] + d[3] * d[3]; }
;             const float rstd = rsqrtf(wave_sum(q) * (1.f / 1024.f) + 1e-5f);
; #pragma unroll
;             for (int i = 0; i < 4; ++i) { const int col = lane * 4 + 256 * i; const f32x4 g = *(const f32x4*)(gam + col), b = *(const f32x4*)(bet + col);
;                 v[i] = (v[i] - mean) * rstd * g + b;
;                 if (fin) *(f32x4*)(c->out + (size_t)r * DM + col) = v[i];
;                 else { u32x2 w; w.x = pk2(v[i][0], v[i][1]); w.y = pk2(v[i][2], v[i][3]); *(u32x2*)(XB + (size_t)r * DM + col) = w; } }
;         }
;         if (modsc) { const int mr = modrow_of(r);
; #pragma unroll
;             for (int i = 0; i < 4; ++i) { const int col = lane * 4 + 256 * i; const f32x4 sc = *(const f32x4*)(modsc + (size_t)mr * 12288 + col), sh = *(const f32x4*)(modsh + (size_t)mr * 12288 + col);
;                 const f32x4 h = v[i] * (sc + 1.0f) + sh; u32x2 w; w.x = pk2(h[0], h[1]); w.y = pk2(h[2], h[3]);
;                 *(u32x2*)(H + (size_t)r * DM + col) = w; } }
	v_add_f32_e32 v0, v0, v14
	v_fmac_f32_e32 v140, 0xba800000, v0
	v_fmac_f32_e32 v141, 0xba800000, v0
	v_fmac_f32_e32 v142, 0xba800000, v0
	v_fmac_f32_e32 v143, 0xba800000, v0
	v_fmac_f32_e32 v144, 0xba800000, v0
	v_fmac_f32_e32 v145, 0xba800000, v0
	v_fmac_f32_e32 v146, 0xba800000, v0
	v_fmac_f32_e32 v147, 0xba800000, v0
	v_fmac_f32_e32 v148, 0xba800000, v0
	v_fmac_f32_e32 v149, 0xba800000, v0
	v_fmac_f32_e32 v150, 0xba800000, v0
	v_fmac_f32_e32 v151, 0xba800000, v0
	v_fmac_f32_e32 v152, 0xba800000, v0
	v_fmac_f32_e32 v153, 0xba800000, v0
	v_fmac_f32_e32 v154, 0xba800000, v0
	v_fmac_f32_e32 v155, 0xba800000, v0
	v_mul_f32_e32 v15, v140, v140
	v_fmac_f32_e32 v15, v141, v141
	v_fmac_f32_e32 v15, v142, v142
	v_fmac_f32_e32 v15, v143, v143
	v_fmac_f32_e32 v15, v144, v144
	v_fmac_f32_e32 v15, v145, v145
	v_fmac_f32_e32 v15, v146, v146
	v_fmac_f32_e32 v15, v147, v147
	v_fmac_f32_e32 v15, v148, v148
	v_fmac_f32_e32 v15, v149, v149
	v_fmac_f32_e32 v15, v150, v150
	v_fmac_f32_e32 v15, v151, v151
	v_fmac_f32_e32 v15, v152, v152
	v_fmac_f32_e32 v15, v153, v153
	v_fmac_f32_e32 v15, v154, v154
	v_fmac_f32_e32 v15, v155, v155
	ds_bpermute_b32 v14, v31, v15
	s_waitcnt lgkmcnt(0)
	v_add_f32_e32 v15, v15, v14
	ds_bpermute_b32 v14, v32, v15
	s_waitcnt lgkmcnt(0)
	v_add_f32_e32 v15, v15, v14
	ds_bpermute_b32 v14, v33, v15
	s_waitcnt lgkmcnt(0)
	v_add_f32_e32 v15, v15, v14
	ds_bpermute_b32 v14, v34, v15
	s_waitcnt lgkmcnt(0)
	v_add_f32_e32 v15, v15, v14
	ds_bpermute_b32 v14, v35, v15
	s_waitcnt lgkmcnt(0)
	v_add_f32_e32 v15, v15, v14
	ds_bpermute_b32 v14, v36, v15
	s_waitcnt lgkmcnt(0)
	v_add_f32_e32 v15, v15, v14
	v_fmamk_f32 v15, v15, 0x3a800000, v189
	v_rsq_f32_e32 v15, v15
	s_nop 0
	v_mul_f32_e32 v140, v140, v15
	v_mul_f32_e32 v141, v141, v15
	v_mul_f32_e32 v142, v142, v15
	v_mul_f32_e32 v143, v143, v15
	v_mul_f32_e32 v144, v144, v15
	v_mul_f32_e32 v145, v145, v15
	v_mul_f32_e32 v146, v146, v15
	v_mul_f32_e32 v147, v147, v15
	v_mul_f32_e32 v148, v148, v15
	v_mul_f32_e32 v149, v149, v15
	v_mul_f32_e32 v150, v150, v15
	v_mul_f32_e32 v151, v151, v15
	v_mul_f32_e32 v152, v152, v15
	v_mul_f32_e32 v153, v153, v15
	v_mul_f32_e32 v154, v154, v15
	v_mul_f32_e32 v155, v155, v15
	v_fma_f32 v140, v60, v140, v76
	v_fma_f32 v141, v61, v141, v77
	v_fma_f32 v142, v62, v142, v78
	v_fma_f32 v143, v63, v143, v79
	v_fma_f32 v144, v64, v144, v80
	v_fma_f32 v145, v65, v145, v81
	v_fma_f32 v146, v66, v146, v82
	v_fma_f32 v147, v67, v147, v83
	v_fma_f32 v148, v68, v148, v84
	v_fma_f32 v149, v69, v149, v85
	v_fma_f32 v150, v70, v150, v86
	v_fma_f32 v151, v71, v151, v87
	v_fma_f32 v152, v72, v152, v88
	v_fma_f32 v153, v73, v153, v89
	v_fma_f32 v154, v74, v154, v90
	v_fma_f32 v155, v75, v155, v91
	v_cvt_pk_bf16_f32 v16, v140, v141
	v_cvt_pk_bf16_f32 v17, v142, v143
	global_store_dwordx2 v[12:13], v[16:17], off
	v_cvt_pk_bf16_f32 v18, v144, v145
	v_cvt_pk_bf16_f32 v19, v146, v147
	global_store_dwordx2 v[12:13], v[18:19], off offset:512
	v_cvt_pk_bf16_f32 v20, v148, v149
	v_cvt_pk_bf16_f32 v21, v150, v151
	global_store_dwordx2 v[12:13], v[20:21], off offset:1024
	v_cvt_pk_bf16_f32 v22, v152, v153
	v_cvt_pk_bf16_f32 v23, v154, v155
	global_store_dwordx2 v[12:13], v[22:23], off offset:1536
	s_waitcnt vmcnt(8)
	v_add_f32_e32 v108, 1.0, v108
	v_add_f32_e32 v109, 1.0, v109
	v_add_f32_e32 v110, 1.0, v110
	v_add_f32_e32 v111, 1.0, v111
	v_add_f32_e32 v112, 1.0, v112
	v_add_f32_e32 v113, 1.0, v113
	v_add_f32_e32 v114, 1.0, v114
	v_add_f32_e32 v115, 1.0, v115
	v_add_f32_e32 v116, 1.0, v116
	v_add_f32_e32 v117, 1.0, v117
	v_add_f32_e32 v118, 1.0, v118
	v_add_f32_e32 v119, 1.0, v119
	v_add_f32_e32 v120, 1.0, v120
	v_add_f32_e32 v121, 1.0, v121
	v_add_f32_e32 v122, 1.0, v122
	v_add_f32_e32 v123, 1.0, v123
	v_fma_f32 v108, v108, v140, v124
	v_fma_f32 v109, v109, v141, v125
	v_fma_f32 v110, v110, v142, v126
	v_fma_f32 v111, v111, v143, v127
	v_fma_f32 v112, v112, v144, v128
	v_fma_f32 v113, v113, v145, v129
	v_fma_f32 v114, v114, v146, v130
	v_fma_f32 v115, v115, v147, v131
	v_fma_f32 v116, v116, v148, v132
	v_fma_f32 v117, v117, v149, v133
	v_fma_f32 v118, v118, v150, v134
	v_fma_f32 v119, v119, v151, v135
	v_fma_f32 v120, v120, v152, v136
	v_fma_f32 v121, v121, v153, v137
	v_fma_f32 v122, v122, v154, v138
	v_fma_f32 v123, v123, v155, v139
	v_cvt_pk_bf16_f32 v50, v108, v109
	v_cvt_pk_bf16_f32 v51, v110, v111
	global_store_dwordx2 v[10:11], v[50:51], off
	v_cvt_pk_bf16_f32 v52, v112, v113
	v_cvt_pk_bf16_f32 v53, v114, v115
	global_store_dwordx2 v[10:11], v[52:53], off offset:512
	v_cvt_pk_bf16_f32 v54, v116, v117
	v_cvt_pk_bf16_f32 v55, v118, v119
	global_store_dwordx2 v[10:11], v[54:55], off offset:1024
	v_cvt_pk_bf16_f32 v56, v120, v121
	v_cvt_pk_bf16_f32 v57, v122, v123
	global_store_dwordx2 v[10:11], v[56:57], off offset:1536
	v_add_u32_e32 v30, s76, v30
	v_mov_b32_e32 v12, v48
	v_mov_b32_e32 v13, v49
	v_lshl_add_u64 v[10:11], v[10:11], 0, s[44:45]
	v_cmp_lt_i32_e32 vcc, s81, v30
	s_or_b64 s[6:7], vcc, s[6:7]
	s_andn2_b64 exec, exec, s[6:7]
	s_cbranch_execz .LBB0_416
; DI float lo16(unsigned w) { return __uint_as_float(w << 16); }
; DI float hi16(unsigned w) { return __uint_as_float(w & 0xffff0000u); }
; DI float wave_sum(float v) { for (int o = 32; o >= 1; o >>= 1) v += __shfl_xor(v, o); return v; }
; DI void ln_pass(CP c, int mode, const float* gam, const float* bet, const float* modsc, const float* modsh, int bid, int nb, bool fin) {
;     ...
;     for (int r = bid * 8 + wave; r < MT; r += nb * 8) {
;         f32x4 v[4];
;         if (mode == 0) { const float* src = r < MP ? c->in[I_XP] + (size_t)r * DM : c->in[I_XS] + (size_t)(r - MP) * DM;
; #pragma unroll
;             for (int i = 0; i < 4; ++i) v[i] = *(const f32x4*)(src + lane * 4 + 256 * i); }
;         else {
; #pragma unroll
;             for (int i = 0; i < 4; ++i) { const u32x2 w = *(const u32x2*)(XB + (size_t)r * DM + lane * 4 + 256 * i); v[i] = (f32x4){lo16(w.x), hi16(w.x), lo16(w.y), hi16(w.y)}; } }
;         if (mode != 1) {
;             float s = 0.f;
; #pragma unroll
;             for (int i = 0; i < 4; ++i) s += v[i][0] + v[i][1] + v[i][2] + v[i][3];
;             const float mean = wave_sum(s) * (1.f / 1024.f); float q = 0.f;
; #pragma unroll
;             for (int i = 0; i < 4; ++i) { const f32x4 d = v[i] - mean; q += d[0] * d[0] + d[1] * d[1] + d[2] * d[2] + d[3] * d[3]; }
;             const float rstd = rsqrtf(wave_sum(q) * (1.f / 1024.f) + 1e-5f);
	v_add_u32_e32 v0, 0xffffc000, v30
	v_lshrrev_b32_e32 v0, 4, v0
	v_add_u32_e32 v0, 1, v0
	v_cmp_lt_i32_e32 vcc, s3, v30
	s_nop 1
	v_cndmask_b32_e32 v0, 0, v0, vcc
	v_mad_u64_u32 v[24:25], s[8:9], v0, s86, v[6:7]
	v_mad_u64_u32 v[46:47], s[8:9], v0, s86, v[8:9]
	global_load_dwordx4 v[108:111], v[24:25], off
	global_load_dwordx4 v[112:115], v[24:25], off offset:1024
	global_load_dwordx4 v[116:119], v[24:25], off offset:2048
	global_load_dwordx4 v[120:123], v[24:25], off offset:3072
	global_load_dwordx4 v[124:127], v[46:47], off
	global_load_dwordx4 v[128:131], v[46:47], off offset:1024
	global_load_dwordx4 v[132:135], v[46:47], off offset:2048
	global_load_dwordx4 v[136:139], v[46:47], off offset:3072
	s_waitcnt vmcnt(8)
	v_lshl_add_u64 v[48:49], v[12:13], 0, s[44:45]
	global_load_dwordx2 v[92:93], v[48:49], off
	global_load_dwordx2 v[94:95], v[48:49], off offset:512
	global_load_dwordx2 v[96:97], v[48:49], off offset:1024
	global_load_dwordx2 v[98:99], v[48:49], off offset:1536
	v_lshlrev_b32_e32 v140, 16, v100
	v_and_b32_e32 v141, 0xffff0000, v100
	v_lshlrev_b32_e32 v142, 16, v101
	v_and_b32_e32 v143, 0xffff0000, v101
	v_lshlrev_b32_e32 v144, 16, v102
	v_and_b32_e32 v145, 0xffff0000, v102
	v_lshlrev_b32_e32 v146, 16, v103
	v_and_b32_e32 v147, 0xffff0000, v103
	v_lshlrev_b32_e32 v148, 16, v104
	v_and_b32_e32 v149, 0xffff0000, v104
	v_lshlrev_b32_e32 v150, 16, v105
	v_and_b32_e32 v151, 0xffff0000, v105
	v_lshlrev_b32_e32 v152, 16, v106
	v_and_b32_e32 v153, 0xffff0000, v106
	v_lshlrev_b32_e32 v154, 16, v107
	v_and_b32_e32 v155, 0xffff0000, v107
	v_add_f32_e32 v0, v140, v141
	v_add_f32_e32 v0, v0, v142
	v_add_f32_e32 v0, v0, v143
	v_add_f32_e32 v0, v0, v144
	v_add_f32_e32 v0, v0, v145
	v_add_f32_e32 v0, v0, v146
	v_add_f32_e32 v0, v0, v147
	v_add_f32_e32 v0, v0, v148
	v_add_f32_e32 v0, v0, v149
	v_add_f32_e32 v0, v0, v150
	v_add_f32_e32 v0, v0, v151
	v_add_f32_e32 v0, v0, v152
	v_add_f32_e32 v0, v0, v153
	v_add_f32_e32 v0, v0, v154
	v_add_f32_e32 v0, v0, v155
	ds_bpermute_b32 v14, v31, v0
	s_waitcnt lgkmcnt(0)
	v_add_f32_e32 v0, v0, v14
	ds_bpermute_b32 v14, v32, v0
	s_waitcnt lgkmcnt(0)
	v_add_f32_e32 v0, v0, v14
	ds_bpermute_b32 v14, v33, v0
	s_waitcnt lgkmcnt(0)
	v_add_f32_e32 v0, v0, v14
	ds_bpermute_b32 v14, v34, v0
	s_waitcnt lgkmcnt(0)
	v_add_f32_e32 v0, v0, v14
	ds_bpermute_b32 v14, v35, v0
	s_waitcnt lgkmcnt(0)
	v_add_f32_e32 v0, v0, v14
	ds_bpermute_b32 v14, v36, v0
	s_waitcnt lgkmcnt(0)
	v_add_f32_e32 v0, v0, v14
	v_fmac_f32_e32 v140, 0xba800000, v0
	v_fmac_f32_e32 v141, 0xba800000, v0
	v_fmac_f32_e32 v142, 0xba800000, v0
	v_fmac_f32_e32 v143, 0xba800000, v0
	v_fmac_f32_e32 v144, 0xba800000, v0
	v_fmac_f32_e32 v145, 0xba800000, v0
	v_fmac_f32_e32 v146, 0xba800000, v0
	v_fmac_f32_e32 v147, 0xba800000, v0
	v_fmac_f32_e32 v148, 0xba800000, v0
	v_fmac_f32_e32 v149, 0xba800000, v0
	v_fmac_f32_e32 v150, 0xba800000, v0
	v_fmac_f32_e32 v151, 0xba800000, v0
	v_fmac_f32_e32 v152, 0xba800000, v0
	v_fmac_f32_e32 v153, 0xba800000, v0
	v_fmac_f32_e32 v154, 0xba800000, v0
	v_fmac_f32_e32 v155, 0xba800000, v0
	v_mul_f32_e32 v15, v140, v140
	v_fmac_f32_e32 v15, v141, v141
	v_fmac_f32_e32 v15, v142, v142
	v_fmac_f32_e32 v15, v143, v143
	v_fmac_f32_e32 v15, v144, v144
	v_fmac_f32_e32 v15, v145, v145
	v_fmac_f32_e32 v15, v146, v146
	v_fmac_f32_e32 v15, v147, v147
	v_fmac_f32_e32 v15, v148, v148
	v_fmac_f32_e32 v15, v149, v149
	v_fmac_f32_e32 v15, v150, v150
	v_fmac_f32_e32 v15, v151, v151
	v_fmac_f32_e32 v15, v152, v152
	v_fmac_f32_e32 v15, v153, v153
	v_fmac_f32_e32 v15, v154, v154
	v_fmac_f32_e32 v15, v155, v155
	ds_bpermute_b32 v14, v31, v15
	s_waitcnt lgkmcnt(0)
	v_add_f32_e32 v15, v15, v14
	ds_bpermute_b32 v14, v32, v15
	s_waitcnt lgkmcnt(0)
; DI unsigned pk2(float lo, float hi) { const hwf2_t v = {lo, hi}; const hwbf2_t b = __builtin_convertvector(v, hwbf2_t); return __builtin_bit_cast(unsigned, b); }
; DI float wave_sum(float v) { for (int o = 32; o >= 1; o >>= 1) v += __shfl_xor(v, o); return v; }
; DI void ln_pass(CP c, int mode, const float* gam, const float* bet, const float* modsc, const float* modsh, int bid, int nb, bool fin) {
;     ...
;             const float rstd = rsqrtf(wave_sum(q) * (1.f / 1024.f) + 1e-5f);
; #pragma unroll
;             for (int i = 0; i < 4; ++i) { const int col = lane * 4 + 256 * i; const f32x4 g = *(const f32x4*)(gam + col), b = *(const f32x4*)(bet + col);
;                 v[i] = (v[i] - mean) * rstd * g + b;
;                 if (fin) *(f32x4*)(c->out + (size_t)r * DM + col) = v[i];
;                 else { u32x2 w; w.x = pk2(v[i][0], v[i][1]); w.y = pk2(v[i][2], v[i][3]); *(u32x2*)(XB + (size_t)r * DM + col) = w; } }
;         }
;         if (modsc) { const int mr = modrow_of(r);
; #pragma unroll
;             for (int i = 0; i < 4; ++i) { const int col = lane * 4 + 256 * i; const f32x4 sc = *(const f32x4*)(modsc + (size_t)mr * 12288 + col), sh = *(const f32x4*)(modsh + (size_t)mr * 12288 + col);
;                 const f32x4 h = v[i] * (sc + 1.0f) + sh; u32x2 w; w.x = pk2(h[0], h[1]); w.y = pk2(h[2], h[3]);
;                 *(u32x2*)(H + (size_t)r * DM + col) = w; } }
	v_add_f32_e32 v15, v15, v14
	ds_bpermute_b32 v14, v33, v15
	s_waitcnt lgkmcnt(0)
	v_add_f32_e32 v15, v15, v14
	ds_bpermute_b32 v14, v34, v15
	s_waitcnt lgkmcnt(0)
	v_add_f32_e32 v15, v15, v14
	ds_bpermute_b32 v14, v35, v15
	s_waitcnt lgkmcnt(0)
	v_add_f32_e32 v15, v15, v14
	ds_bpermute_b32 v14, v36, v15
	s_waitcnt lgkmcnt(0)
	v_add_f32_e32 v15, v15, v14
	v_fmamk_f32 v15, v15, 0x3a800000, v189
	v_rsq_f32_e32 v15, v15
	s_nop 0
	v_mul_f32_e32 v140, v140, v15
	v_mul_f32_e32 v141, v141, v15
	v_mul_f32_e32 v142, v142, v15
	v_mul_f32_e32 v143, v143, v15
	v_mul_f32_e32 v144, v144, v15
	v_mul_f32_e32 v145, v145, v15
	v_mul_f32_e32 v146, v146, v15
	v_mul_f32_e32 v147, v147, v15
	v_mul_f32_e32 v148, v148, v15
	v_mul_f32_e32 v149, v149, v15
	v_mul_f32_e32 v150, v150, v15
	v_mul_f32_e32 v151, v151, v15
	v_mul_f32_e32 v152, v152, v15
	v_mul_f32_e32 v153, v153, v15
	v_mul_f32_e32 v154, v154, v15
	v_mul_f32_e32 v155, v155, v15
	v_fma_f32 v140, v60, v140, v76
	v_fma_f32 v141, v61, v141, v77
	v_fma_f32 v142, v62, v142, v78
	v_fma_f32 v143, v63, v143, v79
	v_fma_f32 v144, v64, v144, v80
	v_fma_f32 v145, v65, v145, v81
	v_fma_f32 v146, v66, v146, v82
	v_fma_f32 v147, v67, v147, v83
	v_fma_f32 v148, v68, v148, v84
	v_fma_f32 v149, v69, v149, v85
	v_fma_f32 v150, v70, v150, v86
	v_fma_f32 v151, v71, v151, v87
	v_fma_f32 v152, v72, v152, v88
	v_fma_f32 v153, v73, v153, v89
	v_fma_f32 v154, v74, v154, v90
	v_fma_f32 v155, v75, v155, v91
	v_cvt_pk_bf16_f32 v16, v140, v141
	v_cvt_pk_bf16_f32 v17, v142, v143
	global_store_dwordx2 v[12:13], v[16:17], off
	v_cvt_pk_bf16_f32 v18, v144, v145
	v_cvt_pk_bf16_f32 v19, v146, v147
	global_store_dwordx2 v[12:13], v[18:19], off offset:512
	v_cvt_pk_bf16_f32 v20, v148, v149
	v_cvt_pk_bf16_f32 v21, v150, v151
	global_store_dwordx2 v[12:13], v[20:21], off offset:1024
	v_cvt_pk_bf16_f32 v22, v152, v153
	v_cvt_pk_bf16_f32 v23, v154, v155
	global_store_dwordx2 v[12:13], v[22:23], off offset:1536
	s_waitcnt vmcnt(8)
	v_add_f32_e32 v108, 1.0, v108
	v_add_f32_e32 v109, 1.0, v109
	v_add_f32_e32 v110, 1.0, v110
	v_add_f32_e32 v111, 1.0, v111
	v_add_f32_e32 v112, 1.0, v112
	v_add_f32_e32 v113, 1.0, v113
	v_add_f32_e32 v114, 1.0, v114
	v_add_f32_e32 v115, 1.0, v115
	v_add_f32_e32 v116, 1.0, v116
	v_add_f32_e32 v117, 1.0, v117
	v_add_f32_e32 v118, 1.0, v118
	v_add_f32_e32 v119, 1.0, v119
	v_add_f32_e32 v120, 1.0, v120
	v_add_f32_e32 v121, 1.0, v121
	v_add_f32_e32 v122, 1.0, v122
	v_add_f32_e32 v123, 1.0, v123
	v_fma_f32 v108, v108, v140, v124
	v_fma_f32 v109, v109, v141, v125
	v_fma_f32 v110, v110, v142, v126
	v_fma_f32 v111, v111, v143, v127
	v_fma_f32 v112, v112, v144, v128
	v_fma_f32 v113, v113, v145, v129
	v_fma_f32 v114, v114, v146, v130
	v_fma_f32 v115, v115, v147, v131
	v_fma_f32 v116, v116, v148, v132
	v_fma_f32 v117, v117, v149, v133
	v_fma_f32 v118, v118, v150, v134
	v_fma_f32 v119, v119, v151, v135
	v_fma_f32 v120, v120, v152, v136
	v_fma_f32 v121, v121, v153, v137
	v_fma_f32 v122, v122, v154, v138
	v_fma_f32 v123, v123, v155, v139
	v_cvt_pk_bf16_f32 v50, v108, v109
	v_cvt_pk_bf16_f32 v51, v110, v111
	global_store_dwordx2 v[10:11], v[50:51], off
	v_cvt_pk_bf16_f32 v52, v112, v113
	v_cvt_pk_bf16_f32 v53, v114, v115
	global_store_dwordx2 v[10:11], v[52:53], off offset:512
	v_cvt_pk_bf16_f32 v54, v116, v117
	v_cvt_pk_bf16_f32 v55, v118, v119
	global_store_dwordx2 v[10:11], v[54:55], off offset:1024
	v_cvt_pk_bf16_f32 v56, v120, v121
	v_cvt_pk_bf16_f32 v57, v122, v123
	global_store_dwordx2 v[10:11], v[56:57], off offset:1536
	v_add_u32_e32 v30, s76, v30
	v_mov_b32_e32 v12, v48
	v_mov_b32_e32 v13, v49
	v_lshl_add_u64 v[10:11], v[10:11], 0, s[44:45]
	v_cmp_lt_i32_e32 vcc, s81, v30
	s_or_b64 s[6:7], vcc, s[6:7]
	s_andn2_b64 exec, exec, s[6:7]
	s_cbranch_execnz .LBB0_415

; DI unsigned pk2(float lo, float hi) { const hwf2_t v = {lo, hi}; const hwbf2_t b = __builtin_convertvector(v, hwbf2_t); return __builtin_bit_cast(unsigned, b); }
; DI float lo16(unsigned w) { return __uint_as_float(w << 16); }
; DI float hi16(unsigned w) { return __uint_as_float(w & 0xffff0000u); }
; DI float wave_sum(float v) { for (int o = 32; o >= 1; o >>= 1) v += __shfl_xor(v, o); return v; }
; DI void ln_pass(CP c, int mode, const float* gam, const float* bet, const float* modsc, const float* modsh, int bid, int nb, bool fin) {
;     ...
;     for (int r = bid * 8 + wave; r < MT; r += nb * 8) {
;         f32x4 v[4];
;         if (mode == 0) { const float* src = r < MP ? c->in[I_XP] + (size_t)r * DM : c->in[I_XS] + (size_t)(r - MP) * DM;
; #pragma unroll
;             for (int i = 0; i < 4; ++i) v[i] = *(const f32x4*)(src + lane * 4 + 256 * i); }
;         else {
; #pragma unroll
;             for (int i = 0; i < 4; ++i) { const u32x2 w = *(const u32x2*)(XB + (size_t)r * DM + lane * 4 + 256 * i); v[i] = (f32x4){lo16(w.x), hi16(w.x), lo16(w.y), hi16(w.y)}; } }
;         if (mode != 1) {
;             float s = 0.f;
; #pragma unroll
;             for (int i = 0; i < 4; ++i) s += v[i][0] + v[i][1] + v[i][2] + v[i][3];
;             const float mean = wave_sum(s) * (1.f / 1024.f); float q = 0.f;
; #pragma unroll
;             for (int i = 0; i < 4; ++i) { const f32x4 d = v[i] - mean; q += d[0] * d[0] + d[1] * d[1] + d[2] * d[2] + d[3] * d[3]; }
;             const float rstd = rsqrtf(wave_sum(q) * (1.f / 1024.f) + 1e-5f);
; #pragma unroll
;             for (int i = 0; i < 4; ++i) { const int col = lane * 4 + 256 * i; const f32x4 g = *(const f32x4*)(gam + col), b = *(const f32x4*)(bet + col);
;                 v[i] = (v[i] - mean) * rstd * g + b;
;                 if (fin) *(f32x4*)(c->out + (size_t)r * DM + col) = v[i];
;                 else { u32x2 w; w.x = pk2(v[i][0], v[i][1]); w.y = pk2(v[i][2], v[i][3]); *(u32x2*)(XB + (size_t)r * DM + col) = w; } }
;         }
;         if (modsc) { const int mr = modrow_of(r);
; #pragma unroll
;             for (int i = 0; i < 4; ++i) { const int col = lane * 4 + 256 * i; const f32x4 sc = *(const f32x4*)(modsc + (size_t)mr * 12288 + col), sh = *(const f32x4*)(modsh + (size_t)mr * 12288 + col);
.LBB0_491:
	s_andn2_b64 vcc, exec, s[6:7]
	s_cbranch_vccnz .LBB0_497
	s_cmp_eq_u32 s80, 7
	s_cbranch_scc0 .LBB0_497
	v_mov_b32_e32 v12, v188
	v_readlane_b32 s0, v252, 39
	s_waitcnt vmcnt(0)
	v_ashrrev_i32_e32 v10, 6, v12
	v_readlane_b32 s1, v252, 40
	v_add_u32_e32 v30, s0, v10
	s_movk_i32 s0, 0x4200
	v_cmp_gt_i32_e32 vcc, s0, v30
	s_and_saveexec_b64 s[0:1], vcc
	s_mov_b32 s14, 0x800000
	s_cbranch_execz .LBB0_496
	v_and_b32_e32 v6, 64, v196
	v_add_u32_e32 v6, 64, v6
	v_xor_b32_e32 v7, 32, v196
	v_cmp_lt_i32_e32 vcc, v7, v6
	v_readlane_b32 s6, v254, 32
	v_readlane_b32 s7, v254, 33
	v_cndmask_b32_e32 v7, v196, v7, vcc
	v_lshlrev_b32_e32 v31, 2, v7
	v_xor_b32_e32 v7, 16, v196
	v_cmp_lt_i32_e32 vcc, v7, v6
	s_lshl_b64 s[6:7], s[6:7], 2
	v_readlane_b32 s8, v254, 34
	v_cndmask_b32_e32 v7, v196, v7, vcc
	v_lshlrev_b32_e32 v32, 2, v7
	v_xor_b32_e32 v7, 8, v196
	v_cmp_lt_i32_e32 vcc, v7, v6
	s_load_dwordx4 s[16:19], s[46:47], 0xe8
	v_readlane_b32 s9, v254, 35
	v_cndmask_b32_e32 v7, v196, v7, vcc
	v_lshlrev_b32_e32 v33, 2, v7
	v_xor_b32_e32 v7, 4, v196
	v_cmp_lt_i32_e32 vcc, v7, v6
	s_add_u32 s6, s8, s6
	s_addc_u32 s7, s9, s7
	v_cndmask_b32_e32 v7, v196, v7, vcc
	v_lshlrev_b32_e32 v34, 2, v7
	v_xor_b32_e32 v7, 2, v196
	v_cmp_lt_i32_e32 vcc, v7, v6
	v_readlane_b32 s8, v254, 30
	v_readlane_b32 s9, v254, 31
	v_cndmask_b32_e32 v7, v196, v7, vcc
	s_lshl_b32 s8, s8, 10
	v_lshlrev_b32_e32 v0, 4, v12
	v_lshlrev_b32_e32 v35, 2, v7
	v_xor_b32_e32 v7, 1, v196
	s_ashr_i32 s9, s8, 31
	v_and_b32_e32 v0, 0x3f0, v0
	v_cmp_lt_i32_e32 vcc, v7, v6
	s_lshl_b64 s[8:9], s[8:9], 2
	v_lshl_add_u64 v[8:9], s[6:7], 0, v[0:1]
	v_cndmask_b32_e32 v6, v196, v7, vcc
	s_mov_b64 s[6:7], 0x4000
	s_waitcnt lgkmcnt(0)
	s_add_u32 s12, s18, s8
	v_lshlrev_b32_e32 v36, 2, v6
	v_lshl_add_u64 v[6:7], v[8:9], 0, s[6:7]
	s_mov_b64 s[6:7], 0x3000
	s_addc_u32 s13, s19, s9
	v_lshl_add_u64 v[8:9], v[8:9], 0, s[6:7]
	v_readlane_b32 s6, v252, 39
	s_add_u32 s8, s16, s8
	v_ashrrev_i32_e32 v11, 31, v10
	v_readlane_b32 s7, v252, 40
	s_addc_u32 s9, s17, s9
	v_lshl_add_u64 v[2:3], s[8:9], 0, v[0:1]
	v_lshl_add_u64 v[10:11], s[6:7], 0, v[10:11]
	v_lshl_add_u64 v[4:5], s[12:13], 0, v[0:1]
	v_lshlrev_b64 v[10:11], 11, v[10:11]
	v_and_b32_e32 v0, 63, v12
	v_lshl_or_b32 v10, v0, 3, v10
	v_lshl_add_u64 v[10:11], s[20:21], 0, v[10:11]
	s_mov_b64 s[6:7], 0x123c4000
	v_lshl_add_u64 v[10:11], v[10:11], 0, s[6:7]
	s_mov_b64 s[6:7], 0
	global_load_dwordx4 v[60:63], v[2:3], off
	global_load_dwordx4 v[64:67], v[2:3], off offset:1024
	global_load_dwordx4 v[68:71], v[2:3], off offset:2048
	global_load_dwordx4 v[72:75], v[2:3], off offset:3072
	global_load_dwordx4 v[76:79], v[4:5], off
	global_load_dwordx4 v[80:83], v[4:5], off offset:1024
	global_load_dwordx4 v[84:87], v[4:5], off offset:2048
	global_load_dwordx4 v[88:91], v[4:5], off offset:3072
	v_add_co_u32_e32 v12, vcc, 0xa342000, v10
	s_nop 1
	v_addc_co_u32_e32 v13, vcc, 0, v11, vcc
	global_load_dwordx2 v[92:93], v[12:13], off
	global_load_dwordx2 v[94:95], v[12:13], off offset:512
	global_load_dwordx2 v[96:97], v[12:13], off offset:1024
	global_load_dwordx2 v[98:99], v[12:13], off offset:1536
